# counted vmcnt waits: prologue transpose prefetch + flash-attention K/V staging keep next-tile loads in flight
# speedup vs baseline: 1.0036x; 1.0036x over previous
; __device__ __forceinline__ void p0_prologue(Frame& F) {
;     ...
;     { constexpr int TOT = DEPTH * PER_L; int it = gw; TItem A, B; float va[32], vb[32];
;       if (it < TOT) { decode(it, A); titem_load(A, va, F.lane);
;         for (;;) {
;             bool hn = it + NGW < TOT; if (hn) { decode(it + NGW, B); titem_load(B, vb, F.lane); }
;             titem_finish(A, va, scr, F.lane); if (!hn) break; it += NGW;
;             hn = it + NGW < TOT; if (hn) { decode(it + NGW, A); titem_load(A, va, F.lane); }
;             titem_finish(B, vb, scr, F.lane); if (!hn) break; it += NGW; } } }
.Lpro_drain_a:
	s_waitcnt vmcnt(0)
	s_branch .LBB0_63

; #define LAS __attribute__((address_space(3)))
; #define GAS __attribute__((address_space(1)))
; __device__ __forceinline__ unsigned pk4_fp8(float a, float b, float c, float d) { int w = __builtin_amdgcn_cvt_pk_fp8_f32(a, b, 0, false); w = __builtin_amdgcn_cvt_pk_fp8_f32(c, d, w, true); return (unsigned)w; }
; __device__ __forceinline__ void titem_finish(const TItem& t, float (&v)[32], LAS float* scr, int lane) {
;     const int N = t.N, item = t.item; const float* gain = t.gain; bf16_t* WT = t.WT; const int ldwt = t.ldwt, koff = t.koff; unsigned char* W8 = t.W8; const int n8 = t.n8;
;     const int nblk = N / 32, kb = item / nblk, nb = item % nblk, k0 = 64 * kb, n0 = 32 * nb;
;     if (gain) {
; #pragma unroll
;         for (int i = 0; i < 32; ++i) v[i] *= ((const GAS float*)gain)[k0 + 2 * i + (lane >> 5)]; }
; #pragma unroll
;     for (int i = 0; i < 32; ++i) scr[(2 * i + (lane >> 5)) * 33 + (lane & 31)] = v[i];
;     asm volatile("s_waitcnt lgkmcnt(0)" ::: "memory");
;     const int c = lane & 7;
;     if (W8 && n0 >= n8) {
; #pragma unroll
;         for (int j = 0; j < 4; ++j) { const int n = (lane >> 3) + 8 * j; const LAS float* s = scr + (8 * c) * 33 + n;
;             u32x2 o; o.x = pk4_fp8(s[0 * 33] * W8_SCALE, s[1 * 33] * W8_SCALE, s[2 * 33] * W8_SCALE, s[3 * 33] * W8_SCALE); o.y = pk4_fp8(s[4 * 33] * W8_SCALE, s[5 * 33] * W8_SCALE, s[6 * 33] * W8_SCALE, s[7 * 33] * W8_SCALE);
;             *(GAS u32x2*)(W8 + (size_t)(n0 - n8 + n) * DM + k0 + 8 * c) = o; }
.LBB0_65:
	s_or_b64 exec, exec, s[24:25]
	s_mul_i32 s19, s19, s7
	s_sub_i32 s7, s15, s19
	v_add_u32_e32 v126, 0x400, v125
	v_add_u32_e32 v127, 0x800, v125
	v_add_u32_e32 v128, 0xc00, v125
	v_add_u32_e32 v129, 0x1000, v125
	v_add_u32_e32 v130, 0x1400, v125
	v_add_u32_e32 v131, 0x1800, v125
	v_add_u32_e32 v132, 0x1c00, v125
	s_lshl_b32 s19, s7, 5
	s_waitcnt vmcnt(62)
	ds_write2_b32 v125, v50, v51 offset1:66
	s_waitcnt vmcnt(60)
	ds_write2_b32 v125, v52, v53 offset0:132 offset1:198
	s_waitcnt vmcnt(58)
	ds_write2_b32 v126, v56, v57 offset0:8 offset1:74
	s_waitcnt vmcnt(56)
	ds_write2_b32 v126, v58, v59 offset0:140 offset1:206
	s_waitcnt vmcnt(54)
	ds_write2_b32 v127, v60, v61 offset0:16 offset1:82
	s_waitcnt vmcnt(52)
	ds_write2_b32 v127, v62, v63 offset0:148 offset1:214
	s_waitcnt vmcnt(50)
	ds_write2_b32 v128, v64, v65 offset0:24 offset1:90
	s_waitcnt vmcnt(48)
	ds_write2_b32 v128, v66, v67 offset0:156 offset1:222
	s_waitcnt vmcnt(46)
	ds_write2_b32 v129, v68, v69 offset0:32 offset1:98
	s_waitcnt vmcnt(44)
	ds_write2_b32 v129, v70, v71 offset0:164 offset1:230
	s_waitcnt vmcnt(42)
	ds_write2_b32 v130, v72, v73 offset0:40 offset1:106
	s_waitcnt vmcnt(40)
	ds_write2_b32 v130, v74, v75 offset0:172 offset1:238
	s_waitcnt vmcnt(38)
	ds_write2_b32 v131, v76, v77 offset0:48 offset1:114
	s_waitcnt vmcnt(36)
	ds_write2_b32 v131, v78, v79 offset0:180 offset1:246
	s_waitcnt vmcnt(34)
	ds_write2_b32 v132, v80, v81 offset0:56 offset1:122
	s_waitcnt vmcnt(32)
	ds_write2_b32 v132, v82, v83 offset0:188 offset1:254
	s_waitcnt lgkmcnt(0)
	s_cmp_ge_i32 s19, s29
	v_cmp_ne_u64_e32 vcc, 0, v[44:45]
	s_cselect_b64 s[24:25], -1, 0
	s_and_b64 s[24:25], vcc, s[24:25]
	s_and_saveexec_b64 s[36:37], s[24:25]
	s_xor_b64 s[24:25], exec, s[36:37]
	s_cbranch_execz .LBB0_67
	ds_read2_b32 v[134:135], v117 offset1:8
	ds_read2_b32 v[142:143], v117 offset0:33 offset1:41
	ds_read2_b32 v[144:145], v117 offset0:66 offset1:74
	ds_read2_b32 v[146:147], v117 offset0:99 offset1:107
	ds_read2_b32 v[148:149], v117 offset0:132 offset1:140
	ds_read2_b32 v[150:151], v117 offset0:165 offset1:173
	v_mov_b32_e32 v152, v39
	s_waitcnt lgkmcnt(5)
	v_mul_f32_e32 v38, 0x43800000, v134
	s_waitcnt lgkmcnt(4)
	v_mul_f32_e32 v133, 0x43800000, v142
	ds_read2_b32 v[154:155], v117 offset0:198 offset1:206
	ds_read2_b32 v[156:157], v117 offset0:231 offset1:239
	v_cvt_pk_fp8_f32 v152, v38, v133
	s_waitcnt lgkmcnt(3)
	v_mul_f32_e32 v38, 0x43800000, v148
	s_waitcnt lgkmcnt(2)
	v_mul_f32_e32 v133, 0x43800000, v150
	v_mov_b32_e32 v153, v39
	v_cvt_pk_fp8_f32 v153, v38, v133
	v_mul_f32_e32 v134, 0x43800000, v144
	v_mul_f32_e32 v137, 0x43800000, v146
	s_waitcnt lgkmcnt(1)
	v_mul_f32_e32 v38, 0x43800000, v154
	s_waitcnt lgkmcnt(0)
	v_mul_f32_e32 v133, 0x43800000, v156
	v_cvt_pk_fp8_f32 v152, v134, v137 op_sel:[0,0,1]
	v_cvt_pk_fp8_f32 v153, v38, v133 op_sel:[0,0,1]
	v_mul_f32_e32 v38, 0x43800000, v135
	v_mul_f32_e32 v133, 0x43800000, v143
	v_mov_b32_e32 v134, v39
	v_cvt_pk_fp8_f32 v134, v38, v133
	v_mul_f32_e32 v38, 0x43800000, v149
	v_mul_f32_e32 v133, 0x43800000, v151
	v_mov_b32_e32 v135, v39
	v_cvt_pk_fp8_f32 v135, v38, v133
	s_sub_i32 s7, s19, s29
	s_ashr_i32 s23, s22, 31
	v_add_u32_e32 v158, s7, v37
	v_mul_f32_e32 v137, 0x43800000, v145
	v_mul_f32_e32 v142, 0x43800000, v147
	v_mul_f32_e32 v38, 0x43800000, v155
	v_mul_f32_e32 v133, 0x43800000, v157
	v_lshl_add_u64 v[140:141], v[44:45], 0, s[22:23]
	v_ashrrev_i32_e32 v159, 31, v158
	v_cvt_pk_fp8_f32 v134, v137, v142 op_sel:[0,0,1]
	v_cvt_pk_fp8_f32 v135, v38, v133 op_sel:[0,0,1]
	v_add_u32_e32 v142, s7, v118
	v_lshl_add_u64 v[140:141], v[140:141], 0, v[42:43]
	v_lshlrev_b64 v[158:159], 12, v[158:159]
	v_ashrrev_i32_e32 v143, 31, v142
	v_lshl_add_u64 v[158:159], v[140:141], 0, v[158:159]
	v_lshlrev_b64 v[142:143], 12, v[142:143]
	global_store_dwordx2 v[158:159], v[152:153], off
	v_lshl_add_u64 v[142:143], v[140:141], 0, v[142:143]
	ds_read2_b32 v[144:145], v117 offset0:16 offset1:24
	ds_read2_b32 v[146:147], v117 offset0:49 offset1:57
	ds_read2_b32 v[148:149], v117 offset0:82 offset1:90
	global_store_dwordx2 v[142:143], v[134:135], off
	ds_read2_b32 v[134:135], v117 offset0:115 offset1:123
	ds_read2_b32 v[142:143], v117 offset0:148 offset1:156
	ds_read2_b32 v[150:151], v117 offset0:181 offset1:189
	s_waitcnt lgkmcnt(5)
	v_mul_f32_e32 v38, 0x43800000, v144
	s_waitcnt lgkmcnt(4)
	v_mul_f32_e32 v133, 0x43800000, v146
	v_mov_b32_e32 v152, v39
	ds_read2_b32 v[154:155], v117 offset0:214 offset1:222
	ds_read2_b32 v[156:157], v117 offset0:247 offset1:255
	v_cvt_pk_fp8_f32 v152, v38, v133
	s_waitcnt lgkmcnt(3)
	v_mul_f32_e32 v38, 0x43800000, v142
	s_waitcnt lgkmcnt(2)
	v_mul_f32_e32 v133, 0x43800000, v150
	v_mov_b32_e32 v153, v39
	v_cvt_pk_fp8_f32 v153, v38, v133
	v_mul_f32_e32 v137, 0x43800000, v148
	v_mul_f32_e32 v134, 0x43800000, v134
	s_waitcnt lgkmcnt(1)
	v_mul_f32_e32 v38, 0x43800000, v154
	s_waitcnt lgkmcnt(0)
	v_mul_f32_e32 v133, 0x43800000, v156
	v_cvt_pk_fp8_f32 v152, v137, v134 op_sel:[0,0,1]
	v_cvt_pk_fp8_f32 v153, v38, v133 op_sel:[0,0,1]
	v_mul_f32_e32 v38, 0x43800000, v145
	v_mul_f32_e32 v133, 0x43800000, v147
	v_mov_b32_e32 v134, v39
	v_mul_f32_e32 v142, 0x43800000, v135
	v_cvt_pk_fp8_f32 v134, v38, v133
	v_mul_f32_e32 v38, 0x43800000, v143
	v_mul_f32_e32 v133, 0x43800000, v151
	v_mov_b32_e32 v135, v39
	v_cvt_pk_fp8_f32 v135, v38, v133
	v_mul_f32_e32 v137, 0x43800000, v149
	v_mul_f32_e32 v38, 0x43800000, v155
	v_mul_f32_e32 v133, 0x43800000, v157
	v_add_u32_e32 v158, s7, v119
	v_cvt_pk_fp8_f32 v134, v137, v142 op_sel:[0,0,1]
	v_cvt_pk_fp8_f32 v135, v38, v133 op_sel:[0,0,1]
	v_add_u32_e32 v142, s7, v120
	v_ashrrev_i32_e32 v159, 31, v158
	v_ashrrev_i32_e32 v143, 31, v142
	v_lshlrev_b64 v[158:159], 12, v[158:159]
	v_lshlrev_b64 v[142:143], 12, v[142:143]
	v_lshl_add_u64 v[158:159], v[140:141], 0, v[158:159]
	v_lshl_add_u64 v[140:141], v[140:141], 0, v[142:143]
	global_store_dwordx2 v[158:159], v[152:153], off
	global_store_dwordx2 v[140:141], v[134:135], off

; #define LAS __attribute__((address_space(3)))
; #define GAS __attribute__((address_space(1)))
; __device__ __forceinline__ unsigned pk4_fp8(float a, float b, float c, float d) { int w = __builtin_amdgcn_cvt_pk_fp8_f32(a, b, 0, false); w = __builtin_amdgcn_cvt_pk_fp8_f32(c, d, w, true); return (unsigned)w; }
; __device__ __forceinline__ void titem_finish(const TItem& t, float (&v)[32], LAS float* scr, int lane) {
;     const int N = t.N, item = t.item; const float* gain = t.gain; bf16_t* WT = t.WT; const int ldwt = t.ldwt, koff = t.koff; unsigned char* W8 = t.W8; const int n8 = t.n8;
;     const int nblk = N / 32, kb = item / nblk, nb = item % nblk, k0 = 64 * kb, n0 = 32 * nb;
;     if (gain) {
; #pragma unroll
;         for (int i = 0; i < 32; ++i) v[i] *= ((const GAS float*)gain)[k0 + 2 * i + (lane >> 5)]; }
; #pragma unroll
;     for (int i = 0; i < 32; ++i) scr[(2 * i + (lane >> 5)) * 33 + (lane & 31)] = v[i];
;     asm volatile("s_waitcnt lgkmcnt(0)" ::: "memory");
;     const int c = lane & 7;
;     if (W8 && n0 >= n8) {
; #pragma unroll
;         for (int j = 0; j < 4; ++j) { const int n = (lane >> 3) + 8 * j; const LAS float* s = scr + (8 * c) * 33 + n;
;             u32x2 o; o.x = pk4_fp8(s[0 * 33] * W8_SCALE, s[1 * 33] * W8_SCALE, s[2 * 33] * W8_SCALE, s[3 * 33] * W8_SCALE); o.y = pk4_fp8(s[4 * 33] * W8_SCALE, s[5 * 33] * W8_SCALE, s[6 * 33] * W8_SCALE, s[7 * 33] * W8_SCALE);
;             *(GAS u32x2*)(W8 + (size_t)(n0 - n8 + n) * DM + k0 + 8 * c) = o; }
; __device__ __forceinline__ void p0_prologue(Frame& F) {
;     ...
;             titem_finish(A, va, scr, F.lane); if (!hn) break; it += NGW;
;             hn = it + NGW < TOT; if (hn) { decode(it + NGW, A); titem_load(A, va, F.lane); }
;             titem_finish(B, vb, scr, F.lane); if (!hn) break; it += NGW; } } }
.LBB0_95:
	s_or_b64 exec, exec, s[22:23]
	s_mul_i32 s7, s7, s1
	s_sub_i32 s1, s30, s7
	s_lshl_b32 s7, s1, 5
	s_waitcnt vmcnt(62)
	ds_write2_b32 v125, v91, v90 offset1:66
	s_waitcnt vmcnt(60)
	ds_write2_b32 v125, v89, v88 offset0:132 offset1:198
	s_waitcnt vmcnt(58)
	ds_write2_b32 v126, v87, v86 offset0:8 offset1:74
	s_waitcnt vmcnt(56)
	ds_write2_b32 v126, v85, v84 offset0:140 offset1:206
	s_waitcnt vmcnt(54)
	ds_write2_b32 v127, v93, v92 offset0:16 offset1:82
	s_waitcnt vmcnt(52)
	ds_write2_b32 v127, v95, v94 offset0:148 offset1:214
	s_waitcnt vmcnt(50)
	ds_write2_b32 v128, v97, v96 offset0:24 offset1:90
	s_waitcnt vmcnt(48)
	ds_write2_b32 v128, v99, v98 offset0:156 offset1:222
	s_waitcnt vmcnt(46)
	ds_write2_b32 v129, v101, v100 offset0:32 offset1:98
	s_waitcnt vmcnt(44)
	ds_write2_b32 v129, v103, v102 offset0:164 offset1:230
	s_waitcnt vmcnt(42)
	ds_write2_b32 v130, v105, v104 offset0:40 offset1:106
	s_waitcnt vmcnt(40)
	ds_write2_b32 v130, v107, v106 offset0:172 offset1:238
	s_waitcnt vmcnt(38)
	ds_write2_b32 v131, v109, v108 offset0:48 offset1:114
	s_waitcnt vmcnt(36)
	ds_write2_b32 v131, v111, v110 offset0:180 offset1:246
	s_waitcnt vmcnt(34)
	ds_write2_b32 v132, v113, v112 offset0:56 offset1:122
	s_waitcnt vmcnt(32)
	ds_write2_b32 v132, v115, v114 offset0:188 offset1:254
	s_waitcnt lgkmcnt(0)
	s_cmp_ge_i32 s7, s31
	v_cmp_ne_u64_e32 vcc, 0, v[54:55]
	s_cselect_b64 s[22:23], -1, 0
	s_and_b64 s[22:23], vcc, s[22:23]
	s_and_saveexec_b64 s[34:35], s[22:23]
	s_xor_b64 s[22:23], exec, s[34:35]
	s_cbranch_execz .LBB0_97
	ds_read2_b32 v[126:127], v117 offset1:8
	ds_read2_b32 v[130:131], v117 offset0:33 offset1:41
	ds_read2_b32 v[132:133], v117 offset0:66 offset1:74
	ds_read2_b32 v[134:135], v117 offset0:99 offset1:107
	ds_read2_b32 v[140:141], v117 offset0:132 offset1:140
	ds_read2_b32 v[142:143], v117 offset0:165 offset1:173
	v_mov_b32_e32 v144, v39
	s_waitcnt lgkmcnt(5)
	v_mul_f32_e32 v38, 0x43800000, v126
	s_waitcnt lgkmcnt(4)
	v_mul_f32_e32 v126, 0x43800000, v130
	ds_read2_b32 v[146:147], v117 offset0:198 offset1:206
	ds_read2_b32 v[148:149], v117 offset0:231 offset1:239
	v_cvt_pk_fp8_f32 v144, v38, v126
	s_waitcnt lgkmcnt(3)
	v_mul_f32_e32 v38, 0x43800000, v140
	s_waitcnt lgkmcnt(2)
	v_mul_f32_e32 v126, 0x43800000, v142
	v_mov_b32_e32 v145, v39
	v_cvt_pk_fp8_f32 v145, v38, v126
	s_waitcnt lgkmcnt(1)
	v_mul_f32_e32 v38, 0x43800000, v146
	s_waitcnt lgkmcnt(0)
	v_mul_f32_e32 v126, 0x43800000, v148
	v_mul_f32_e32 v130, 0x43800000, v132
	v_mul_f32_e32 v132, 0x43800000, v134
	v_cvt_pk_fp8_f32 v145, v38, v126 op_sel:[0,0,1]
	v_mul_f32_e32 v38, 0x43800000, v127
	v_mul_f32_e32 v127, 0x43800000, v131
	v_mov_b32_e32 v126, v39
	v_cvt_pk_fp8_f32 v144, v130, v132 op_sel:[0,0,1]
	v_cvt_pk_fp8_f32 v126, v38, v127
	v_mul_f32_e32 v38, 0x43800000, v141
	v_mul_f32_e32 v132, 0x43800000, v143
	v_mov_b32_e32 v127, v39
	v_cvt_pk_fp8_f32 v127, v38, v132
	s_sub_i32 s19, s7, s31
	v_mul_f32_e32 v130, 0x43800000, v133
	v_mul_f32_e32 v131, 0x43800000, v135
	s_ashr_i32 s1, s0, 31
	v_add_u32_e32 v150, s19, v37
	v_cvt_pk_fp8_f32 v126, v130, v131 op_sel:[0,0,1]
	v_mul_f32_e32 v38, 0x43800000, v147
	v_mul_f32_e32 v130, 0x43800000, v149
	v_lshl_add_u64 v[128:129], v[54:55], 0, s[0:1]
	v_ashrrev_i32_e32 v151, 31, v150
	v_cvt_pk_fp8_f32 v127, v38, v130 op_sel:[0,0,1]
	v_add_u32_e32 v130, s19, v118
	v_lshl_add_u64 v[128:129], v[128:129], 0, v[42:43]
	v_lshlrev_b64 v[150:151], 12, v[150:151]
	v_ashrrev_i32_e32 v131, 31, v130
	v_lshl_add_u64 v[150:151], v[128:129], 0, v[150:151]
	v_lshlrev_b64 v[130:131], 12, v[130:131]
	global_store_dwordx2 v[150:151], v[144:145], off
	v_lshl_add_u64 v[130:131], v[128:129], 0, v[130:131]
	ds_read2_b32 v[132:133], v117 offset0:16 offset1:24
	ds_read2_b32 v[134:135], v117 offset0:49 offset1:57
	ds_read2_b32 v[140:141], v117 offset0:82 offset1:90
	global_store_dwordx2 v[130:131], v[126:127], off
	ds_read2_b32 v[126:127], v117 offset0:115 offset1:123
	ds_read2_b32 v[130:131], v117 offset0:148 offset1:156
	ds_read2_b32 v[142:143], v117 offset0:181 offset1:189
	s_waitcnt lgkmcnt(5)
	v_mul_f32_e32 v38, 0x43800000, v132
	s_waitcnt lgkmcnt(4)
	v_mul_f32_e32 v132, 0x43800000, v134
	v_mov_b32_e32 v144, v39
	ds_read2_b32 v[146:147], v117 offset0:214 offset1:222
	ds_read2_b32 v[148:149], v117 offset0:247 offset1:255
	v_cvt_pk_fp8_f32 v144, v38, v132
	s_waitcnt lgkmcnt(3)
	v_mul_f32_e32 v38, 0x43800000, v130
	s_waitcnt lgkmcnt(2)
	v_mul_f32_e32 v130, 0x43800000, v142
	v_mov_b32_e32 v145, v39
	v_cvt_pk_fp8_f32 v145, v38, v130
	v_mul_f32_e32 v134, 0x43800000, v140
	v_mul_f32_e32 v126, 0x43800000, v126
	v_cvt_pk_fp8_f32 v144, v134, v126 op_sel:[0,0,1]
	s_waitcnt lgkmcnt(1)
	v_mul_f32_e32 v38, 0x43800000, v146
	s_waitcnt lgkmcnt(0)
	v_mul_f32_e32 v126, 0x43800000, v148
	v_cvt_pk_fp8_f32 v145, v38, v126 op_sel:[0,0,1]
	v_mul_f32_e32 v38, 0x43800000, v133
	v_mul_f32_e32 v130, 0x43800000, v135
	v_mov_b32_e32 v126, v39
	v_mul_f32_e32 v133, 0x43800000, v127
	v_cvt_pk_fp8_f32 v126, v38, v130
	v_mul_f32_e32 v38, 0x43800000, v131
	v_mul_f32_e32 v130, 0x43800000, v143
	v_mov_b32_e32 v127, v39
	v_cvt_pk_fp8_f32 v127, v38, v130
	v_mul_f32_e32 v132, 0x43800000, v141
	v_mul_f32_e32 v38, 0x43800000, v147
	v_mul_f32_e32 v130, 0x43800000, v149
	v_add_u32_e32 v150, s19, v119
	v_cvt_pk_fp8_f32 v126, v132, v133 op_sel:[0,0,1]
	v_cvt_pk_fp8_f32 v127, v38, v130 op_sel:[0,0,1]
	v_add_u32_e32 v130, s19, v120
	v_ashrrev_i32_e32 v151, 31, v150
	v_ashrrev_i32_e32 v131, 31, v130
	v_lshlrev_b64 v[150:151], 12, v[150:151]
	v_lshlrev_b64 v[130:131], 12, v[130:131]
	v_lshl_add_u64 v[150:151], v[128:129], 0, v[150:151]
	v_lshl_add_u64 v[128:129], v[128:129], 0, v[130:131]
	global_store_dwordx2 v[150:151], v[144:145], off
	global_store_dwordx2 v[128:129], v[126:127], off

; #define LAS __attribute__((address_space(3)))
; #define FA_SLOAD(i, j) do { const GAS char* kt = (const GAS char*)U.K + (size_t)(j) * TILE_B; const GAS char* vt = (const GAS char*)U.V + (size_t)(j) * TILE_B; \
;     sv0[i] = *(const GAS bf16x8*)(vt + go0); sv1[i] = *(const GAS bf16x8*)(vt + go1); sk0[i] = *(const GAS bf16x8*)(kt + go0); sk1[i] = *(const GAS bf16x8*)(kt + go1); } while (0)
; template <bool NA2>
; __device__ __forceinline__ void flash_unit(LAS unsigned char* lds, const FlashUnit& U, int tid) {
;     ...
;     const int NT = U.NT;
;     FA_SLOAD(0, 0); if (1 < NT) FA_SLOAD(1, 1);
;     __builtin_amdgcn_sched_barrier(0);
;     if (tid < U.tcnt) ((LAS float*)(lds + U.tblo))[TBL_PAD + tid] = U.tv * 11.313708498984761f;
.Lna_stage1_last:
	s_waitcnt vmcnt(3)
	ds_write_b128 v222, v[142:145] offset:16384
	s_waitcnt vmcnt(2)
	ds_write_b128 v223, v[146:149] offset:16384
	s_waitcnt vmcnt(1)
	ds_write_b128 v224, v[158:161] offset:49152
	s_waitcnt vmcnt(0)
	ds_write_b128 v225, v[162:165] offset:49152
	s_branch .Lna_stage1_join

; template <bool NA2>
; __device__ __forceinline__ void flash_unit(LAS unsigned char* lds, const FlashUnit& U, int tid) {
;     ...
;     for (; j + 1 < NT; j += 2) { FA_TILE(j, 0); FA_TILE(j + 1, 1); }
.LBB0_488:
	s_cmp_gt_u32 s11, 7
	s_cbranch_scc1 .Lna_stage1_last
	s_waitcnt vmcnt(7)
	ds_write_b128 v222, v[142:145] offset:16384
	s_waitcnt vmcnt(6)
	ds_write_b128 v223, v[146:149] offset:16384
	s_waitcnt vmcnt(5)
	ds_write_b128 v224, v[158:161] offset:49152
	s_waitcnt vmcnt(4)
	ds_write_b128 v225, v[162:165] offset:49152
.Lna_stage1_join:
	s_cmp_gt_u32 s11, 6
	s_waitcnt lgkmcnt(0)
	s_barrier
	s_cbranch_scc1 .LBB0_490
	v_add_co_u32_e32 v66, vcc, 0x18000, v190
	s_nop 1
	v_addc_co_u32_e32 v67, vcc, 0, v191, vcc
	v_add_co_u32_e32 v68, vcc, 0x18000, v188
	s_nop 1
	v_addc_co_u32_e32 v69, vcc, 0, v189, vcc
	global_load_dwordx4 v[142:145], v[66:67], off
	global_load_dwordx4 v[146:149], v[68:69], off
	v_add_co_u32_e32 v66, vcc, 0x18000, v186
	s_nop 1
	v_addc_co_u32_e32 v67, vcc, 0, v187, vcc
	v_add_co_u32_e32 v68, vcc, 0x18000, v184
	s_nop 1
	v_addc_co_u32_e32 v69, vcc, 0, v185, vcc
	global_load_dwordx4 v[158:161], v[66:67], off
	global_load_dwordx4 v[162:165], v[68:69], off

; #define LAS __attribute__((address_space(3)))
; #define GAS __attribute__((address_space(1)))
; __device__ __forceinline__ int lane_id_hw() { int l; asm volatile("v_mbcnt_lo_u32_b32 %0, -1, 0\n\tv_mbcnt_hi_u32_b32 %0, -1, %0" : "=v"(l)); return l; }
; template <bool NA2>
; __device__ __forceinline__ void flash_unit(LAS unsigned char* lds, const FlashUnit& U, int tid) {
;     ...
;     const int NT = U.NT;
;     FA_SLOAD(0, 0); if (1 < NT) FA_SLOAD(1, 1);
;     __builtin_amdgcn_sched_barrier(0);
;     if (tid < U.tcnt) ((LAS float*)(lds + U.tblo))[TBL_PAD + tid] = U.tv * 11.313708498984761f;
;     ...
;     if (FLASH_SW && (mask & 2)) for (int i = 0;; ++i) {
;         int u = i * G + F.vcu; if (u >= 1152) break;
;         int bh, blk;
;         if (u < 864) { bh = u / 6; blk = 1 + u % 6; } else { u -= 864; bh = u >> 1; blk = (u & 1) * 7; }
;         const int b = bh / 12, h = bh % 12;
;         const int ln = lane_id_hw(), r32 = ln & 31, hi = ln >> 5;
;         fa::FlashUnit U; U.C = 0.08838834764831845f * LOG2E; U.tblo = fa::OFF_TBL + tpar * 4096; tpar ^= 1; const size_t row0 = (size_t)b * SEQ + blk * 256;
;         const int t0 = 256 * blk, kt0 = (blk == 0) ? 0 : t0 - 128; U.NT = (blk == 0 || blk == 7) ? 6 : 8;
;         const int tq = t0 + 32 * wid + r32;
;         U.Q = F.P + row0 * INW + QB + h * 128; if (GATES_FP8) { const size_t ko = ((size_t)(b * 4 + h / 3) * SEQ + kt0) * 128; U.K = (const bf16_t*)(F.ws + WS_KSW) + ko; U.V = (const bf16_t*)(F.ws + WS_VSW) + ko; }
;         else { U.K = F.P + ((size_t)b * SEQ + kt0) * INW + KB + (h / 3) * 128; U.V = U.K + (VB - KB); } U.Z = F.P + row0 * INW + ZB + h * 128; U.O = F.X + row0 * DM + 1536 + h * 128;
;         const int a = t0 + 32 * wid - 128 - kt0, bnd = t0 + 32 * wid + 159 - kt0; U.jlo = a <= 0 ? 0 : (a >> 6); { const int jh = (bnd >> 6) + 1; U.jhi = jh < U.NT ? jh : U.NT; }
;         U.lane_off = kt0 - tq + 128 + 4 * hi; U.jstride = 64; U.vbase = U.lane_off; U.vstride = 64; U.vlim = 257u;
;         U.m_init = F.sink[l * 12 + h] * LOG2E; U.l_init = 1.f; U.rsl = 0;
;         { const int k = wid * 64 + ln; U.tcnt = 257; U.tv = (k < 257) ? ((const GAS float*)F.t5)[t5_bucket(k - 128) * 12 + h] : 0.f; }
;         if (mask & 8) U.jhi = U.jlo;
;         fa::flash_unit<false>(lds, U, wid * 64 + ln);
.Lsw_stage1_last:
	s_waitcnt vmcnt(3)
	ds_write_b128 v215, v[142:145] offset:16384
	s_waitcnt vmcnt(2)
	ds_write_b128 v216, v[150:153] offset:16384
	s_waitcnt vmcnt(1)
	ds_write_b128 v217, v[158:161] offset:49152
	s_waitcnt vmcnt(0)
	ds_write_b128 v218, v[162:165] offset:49152
	s_branch .Lsw_stage1_join

.LBB0_514:
	s_add_i32 s44, s12, -1
	s_cmp_lt_u32 s44, s83
	s_cselect_b64 s[38:39], -1, 0
	s_cmp_ge_u32 s44, s83
	v_lshl_add_u64 v[188:189], v[174:175], 0, s[24:25]
	v_lshl_add_u64 v[186:187], v[176:177], 0, s[24:25]
	v_lshl_add_u64 v[184:185], v[178:179], 0, s[24:25]
	v_lshl_add_u64 v[182:183], v[180:181], 0, s[24:25]
	s_waitcnt vmcnt(7)
	ds_write_b128 v215, v[134:137]
	s_waitcnt vmcnt(6)
	ds_write_b128 v216, v[138:141]
	s_waitcnt vmcnt(5)
	ds_write_b128 v217, v[146:149] offset:32768
	s_waitcnt vmcnt(4)
	ds_write_b128 v218, v[154:157] offset:32768
	s_waitcnt lgkmcnt(0)
	s_barrier
	s_cbranch_scc1 .LBB0_516
	v_add_co_u32_e32 v66, vcc, 0x8000, v188
	s_nop 1
	v_addc_co_u32_e32 v67, vcc, 0, v189, vcc
	v_add_co_u32_e32 v68, vcc, 0x8000, v186
	s_nop 1
	v_addc_co_u32_e32 v69, vcc, 0, v187, vcc
	global_load_dwordx4 v[134:137], v[66:67], off
	global_load_dwordx4 v[138:141], v[68:69], off
	v_add_co_u32_e32 v66, vcc, 0x8000, v184
	s_nop 1
	v_addc_co_u32_e32 v67, vcc, 0, v185, vcc
	v_add_co_u32_e32 v68, vcc, 0x8000, v182
	s_nop 1
	v_addc_co_u32_e32 v69, vcc, 0, v183, vcc
	global_load_dwordx4 v[146:149], v[66:67], off
	global_load_dwordx4 v[154:157], v[68:69], off

.LBB0_522:
	s_cmp_ge_u32 s12, s83
	s_cselect_b64 s[44:45], -1, 0
	s_and_b64 vcc, exec, s[38:39]
	s_cbranch_vccz .Lsw_stage1_last
	s_waitcnt vmcnt(7)
	ds_write_b128 v215, v[142:145] offset:16384
	s_waitcnt vmcnt(6)
	ds_write_b128 v216, v[150:153] offset:16384
	s_waitcnt vmcnt(5)
	ds_write_b128 v217, v[158:161] offset:49152
	s_waitcnt vmcnt(4)
	ds_write_b128 v218, v[162:165] offset:49152
.Lsw_stage1_join:
	s_and_b64 vcc, exec, s[44:45]
	s_waitcnt lgkmcnt(0)
	s_barrier
	s_cbranch_vccnz .LBB0_524
	v_add_co_u32_e32 v66, vcc, 0xc000, v188
	s_nop 1
	v_addc_co_u32_e32 v67, vcc, 0, v189, vcc
	v_add_co_u32_e32 v68, vcc, 0xc000, v186
	s_nop 1
	v_addc_co_u32_e32 v69, vcc, 0, v187, vcc
	global_load_dwordx4 v[142:145], v[66:67], off
	global_load_dwordx4 v[150:153], v[68:69], off
	v_add_co_u32_e32 v66, vcc, 0xc000, v184
	s_nop 1
	v_addc_co_u32_e32 v67, vcc, 0, v185, vcc
	v_add_co_u32_e32 v68, vcc, 0xc000, v182
	s_nop 1
	v_addc_co_u32_e32 v69, vcc, 0, v183, vcc
	global_load_dwordx4 v[158:161], v[66:67], off
	global_load_dwordx4 v[162:165], v[68:69], off
